# in-proj K-loop body shifted by 4 bytes (unexecuted pad before the loop head and after the back branch): code-placement trial
# baseline (speedup 1.0000x reference)
; #define RAW_BARRIER() do { asm volatile("s_waitcnt lgkmcnt(0)" ::: "memory"); __builtin_amdgcn_s_barrier(); } while (0)
; template <int WM, class Epi>
; DI void gemm_mfma(const bf16_t* __restrict__ A, const bf16_t* __restrict__ Bt, int Arows, int Brows, int MT, int NT, unsigned char* smem, int bid, int nb, int wave, Epi epi) {
;     ...
;   for (int li = l0; li < per; li += lstep) {
;     const int wi = xq * per + li;
;     const int patch = wi / (PM * PN), within = wi % (PM * PN);
;     const int mt = epi.mt_of((patch / NPN) * PM + within / PN), nt = (patch % NPN) * PN + within % PN;
;     f32x16 acc[WM][2];
; #pragma unroll
;     for (int a = 0; a < WM; ++a)
; #pragma unroll
;       for (int b = 0; b < 2; ++b)
; #pragma unroll
;         for (int i = 0; i < 16; ++i) acc[a][b][i] = 0.f;
;     constexpr int NAW = NA / 4;
;     const int wvu = __builtin_amdgcn_readfirstlane(wv);
;     const unsigned voff = (unsigned)((lrow * 32 + ((lpc ^ ((lrow >> 2) & 3)) << 3)) * 2);
;     const char* abase = (const char*)(A + (size_t)(mt * BMROWS + wvu * NAW * 16) * 32);
;     const char* bbase = (const char*)(Bt + (size_t)(nt * 128 + wvu * 2 * 16) * 32);
;     const size_t astep = (size_t)Arows * 64, bstep = (size_t)Brows * 64;
;     auto issue = [&](int kt, int buf) {
; #pragma unroll
;       for (int i = 0; i < NAW; ++i)
;         __builtin_amdgcn_global_load_lds((const unsigned*)(abase + kt * astep + i * 1024 + voff),
;                                          (__attribute__((address_space(3))) unsigned*)(smem + buf * STAGE + (wvu * NAW + i) * 1024), 16, 0, 0);
; #pragma unroll
;       for (int i = 0; i < 2; ++i)
;         __builtin_amdgcn_global_load_lds((const unsigned*)(bbase + kt * bstep + i * 1024 + voff),
;                                          (__attribute__((address_space(3))) unsigned*)(smem + buf * STAGE + A_BYTES + (wvu * 2 + i) * 1024), 16, 0, 0);
;     };
;     RAW_BARRIER();
;     constexpr int NST = (WM == 2) ? 4 : 3;
;     constexpr int NKT = K / 32;
; #pragma unroll
;     for (int s = 0; s < NST - 1; ++s) issue(s, s);
;     bf16x8 fa0[WM], fb0[2], fa1[WM], fb1[2];
; #pragma unroll
;     for (int mi = 0; mi < WM; ++mi) { fa0[mi] = bf16x8{0, 0, 0, 0, 0, 0, 0, 0}; fa1[mi] = fa0[mi]; }
;     fb0[0] = bf16x8{0, 0, 0, 0, 0, 0, 0, 0}; fb0[1] = fb0[0]; fb1[0] = fb0[0]; fb1[1] = fb0[0];
.LBB0_163:
	v_readlane_b32 s0, v254, 0
	s_add_i32 s0, s35, s0
	s_lshr_b32 s1, s0, 2
	s_mul_i32 s1, s1, 0x751
	s_lshr_b32 s1, s1, 16
	s_mul_i32 s4, s1, 0x8c
	s_sub_i32 s0, s0, s4
	s_and_b32 s4, s0, 3
	s_lshr_b32 s0, s0, 2
	s_mov_b32 s29, s0
	s_mov_b32 s8, s0
	v_readfirstlane_b32 s20, v156
	s_lshl_b32 s0, s1, 10
	s_lshl_b32 s28, s4, 8
	s_add_i32 s28, s28, s0
	s_lshl_b32 s0, s20, 6
	s_add_i32 s0, s28, s0
	s_ashr_i32 s1, s0, 31
	s_lshl_b64 s[4:5], s[0:1], 6
	s_add_u32 s6, s2, s4
	s_addc_u32 s7, s30, s5
	s_lshl_b32 s24, s8, 7
	s_lshl_b32 s0, s20, 5
	s_add_i32 s0, s24, s0
	s_ashr_i32 s1, s0, 31
	s_lshl_b64 s[0:1], s[0:1], 6
	s_add_u32 s0, s31, s0
	s_addc_u32 s1, s34, s1
	s_lshl_b32 s9, s20, 12
	v_lshl_add_u64 v[0:1], s[6:7], 0, v[152:153]
	s_mov_b32 m0, s9
	s_mov_b64 s[6:7], 0x400
	s_waitcnt lgkmcnt(0)
	s_barrier
	global_load_lds_dwordx4 v[0:1], off
	v_lshl_add_u64 v[2:3], v[0:1], 0, s[6:7]
	s_or_b32 m0, s9, 0x400
	s_mov_b64 s[26:27], 0x800
	global_load_lds_dwordx4 v[2:3], off
	v_lshl_add_u64 v[2:3], v[0:1], 0, s[26:27]
	s_or_b32 m0, s9, 0x800
	s_mov_b64 s[26:27], 0xc00
	s_lshl_b32 s20, s20, 11
	global_load_lds_dwordx4 v[2:3], off
	v_lshl_add_u64 v[2:3], v[0:1], 0, s[26:27]
	s_or_b32 m0, s9, 0xc00
	v_mov_b32_e32 v128, 0
	global_load_lds_dwordx4 v[2:3], off
	v_lshl_add_u64 v[2:3], s[0:1], 0, v[152:153]
	s_add_i32 m0, s20, 0x4000
	v_lshl_add_u64 v[4:5], v[2:3], 0, s[6:7]
	global_load_lds_dwordx4 v[2:3], off
	s_add_i32 m0, s20, 0x4400
	s_mov_b64 s[6:7], 0x120000
	global_load_lds_dwordx4 v[4:5], off
	v_lshl_add_u64 v[4:5], v[0:1], 0, s[6:7]
	s_add_i32 m0, s9, 0x6000
	s_mov_b64 s[6:7], 0x120400
	global_load_lds_dwordx4 v[4:5], off
	v_lshl_add_u64 v[4:5], v[0:1], 0, s[6:7]
	s_add_i32 m0, s9, 0x6400
	s_mov_b64 s[6:7], 0x120800
	global_load_lds_dwordx4 v[4:5], off
	v_lshl_add_u64 v[4:5], v[0:1], 0, s[6:7]
	s_add_i32 m0, s9, 0x6800
	s_mov_b64 s[6:7], 0x120c00
	global_load_lds_dwordx4 v[4:5], off
	v_lshl_add_u64 v[0:1], v[0:1], 0, s[6:7]
	s_add_i32 m0, s9, 0x6c00
	s_mov_b64 s[6:7], 0x46000
	global_load_lds_dwordx4 v[0:1], off
	v_lshl_add_u64 v[0:1], v[2:3], 0, s[6:7]
	s_add_i32 m0, s20, 0xa000
	s_mov_b64 s[6:7], 0x46400
	global_load_lds_dwordx4 v[0:1], off
	v_lshl_add_u64 v[0:1], v[2:3], 0, s[6:7]
	s_add_i32 m0, s20, 0xa400
	s_add_u32 s4, s68, s4
	global_load_lds_dwordx4 v[0:1], off
	v_mov_b32_e32 v0, 0
	s_addc_u32 s5, s69, s5
	s_mov_b32 s21, 2
	v_mov_b32_e32 v1, v0
	v_mov_b32_e32 v2, v0
	v_mov_b32_e32 v3, v0
	v_mov_b32_e32 v4, v0
	v_mov_b32_e32 v5, v0
	v_mov_b32_e32 v6, v0
	v_mov_b32_e32 v7, v0
	v_mov_b32_e32 v8, v0
	v_mov_b32_e32 v9, v0
	v_mov_b32_e32 v10, v0
	v_mov_b32_e32 v11, v0
	v_mov_b32_e32 v12, v0
	v_mov_b32_e32 v13, v0
	v_mov_b32_e32 v14, v0
	v_mov_b32_e32 v15, v0
	v_mov_b32_e32 v16, v0
	v_mov_b32_e32 v17, v0
	v_mov_b32_e32 v18, v0
	v_mov_b32_e32 v19, v0
	v_mov_b32_e32 v20, v0
	v_mov_b32_e32 v21, v0
	v_mov_b32_e32 v22, v0
	v_mov_b32_e32 v23, v0
	v_mov_b32_e32 v24, v0
	v_mov_b32_e32 v25, v0
	v_mov_b32_e32 v26, v0
	v_mov_b32_e32 v27, v0
	v_mov_b32_e32 v28, v0
	v_mov_b32_e32 v29, v0
	v_mov_b32_e32 v30, v0
	v_mov_b32_e32 v31, v0
	v_mov_b32_e32 v32, v0
	v_mov_b32_e32 v33, v0
	v_mov_b32_e32 v34, v0
	v_mov_b32_e32 v35, v0
	v_mov_b32_e32 v36, v0
	v_mov_b32_e32 v37, v0
	v_mov_b32_e32 v38, v0
	v_mov_b32_e32 v39, v0
	v_mov_b32_e32 v40, v0
	v_mov_b32_e32 v41, v0
	v_mov_b32_e32 v42, v0
	v_mov_b32_e32 v43, v0
	v_mov_b32_e32 v44, v0
	v_mov_b32_e32 v45, v0
	v_mov_b32_e32 v46, v0
	v_mov_b32_e32 v47, v0
	v_mov_b32_e32 v48, v0
	v_mov_b32_e32 v49, v0
	v_mov_b32_e32 v50, v0
	v_mov_b32_e32 v51, v0
	v_mov_b32_e32 v52, v0
	v_mov_b32_e32 v53, v0
	v_mov_b32_e32 v54, v0
	v_mov_b32_e32 v55, v0
	v_mov_b32_e32 v56, v0
	v_mov_b32_e32 v57, v0
	v_mov_b32_e32 v58, v0
	v_mov_b32_e32 v59, v0
	v_mov_b32_e32 v60, v0
	v_mov_b32_e32 v61, v0
	v_mov_b32_e32 v62, v0
	v_mov_b32_e32 v63, v0
	v_mov_b32_e32 v64, v0
	v_mov_b32_e32 v65, v0
	v_mov_b32_e32 v66, v0
	v_mov_b32_e32 v67, v0
	v_mov_b32_e32 v68, v0
	v_mov_b32_e32 v69, v0
	v_mov_b32_e32 v70, v0
	v_mov_b32_e32 v71, v0
	v_mov_b32_e32 v72, v0
	v_mov_b32_e32 v73, v0
	v_mov_b32_e32 v74, v0
	v_mov_b32_e32 v75, v0
	v_mov_b32_e32 v76, v0
	v_mov_b32_e32 v77, v0
	v_mov_b32_e32 v78, v0
	v_mov_b32_e32 v79, v0
	v_mov_b32_e32 v80, v0
	v_mov_b32_e32 v81, v0
	v_mov_b32_e32 v82, v0
	v_mov_b32_e32 v83, v0
	v_mov_b32_e32 v84, v0
	v_mov_b32_e32 v85, v0
	v_mov_b32_e32 v86, v0
	v_mov_b32_e32 v87, v0
	v_mov_b32_e32 v88, v0
	v_mov_b32_e32 v89, v0
	v_mov_b32_e32 v90, v0
	v_mov_b32_e32 v91, v0
	v_mov_b32_e32 v92, v0
	v_mov_b32_e32 v93, v0
	v_mov_b32_e32 v94, v0
	v_mov_b32_e32 v95, v0
	v_mov_b32_e32 v96, v0
	v_mov_b32_e32 v97, v0
	v_mov_b32_e32 v98, v0
	v_mov_b32_e32 v99, v0
	v_mov_b32_e32 v100, v0
	v_mov_b32_e32 v101, v0
	v_mov_b32_e32 v102, v0
	v_mov_b32_e32 v103, v0
	v_mov_b32_e32 v104, v0
	v_mov_b32_e32 v105, v0
	v_mov_b32_e32 v106, v0
	v_mov_b32_e32 v107, v0
	v_mov_b32_e32 v108, v0
	v_mov_b32_e32 v109, v0
	v_mov_b32_e32 v110, v0
	v_mov_b32_e32 v111, v0
	v_mov_b32_e32 v112, v0
	v_mov_b32_e32 v113, v0
	v_mov_b32_e32 v114, v0
	v_mov_b32_e32 v115, v0
	v_mov_b32_e32 v116, v0
	v_mov_b32_e32 v117, v0
	v_mov_b32_e32 v118, v0
	v_mov_b32_e32 v119, v0
	v_mov_b32_e32 v120, v0
	v_mov_b32_e32 v121, v0
	v_mov_b32_e32 v122, v0
	v_mov_b32_e32 v123, v0
	v_mov_b32_e32 v124, v0
	v_mov_b32_e32 v125, v0
	v_mov_b32_e32 v126, v0
	v_mov_b32_e32 v127, v0
	v_mov_b32_e32 v129, v128
	v_mov_b32_e32 v130, v128
	v_mov_b32_e32 v131, v128
	v_mov_b32_e32 v132, v128
	v_mov_b32_e32 v133, v128
	v_mov_b32_e32 v134, v128
	v_mov_b32_e32 v135, v128
	v_mov_b32_e32 v140, v128
	v_mov_b32_e32 v141, v128
	v_mov_b32_e32 v142, v128
	v_mov_b32_e32 v143, v128
	v_mov_b32_e32 v148, v128
	v_mov_b32_e32 v149, v128
	v_mov_b32_e32 v150, v128
	v_mov_b32_e32 v151, v128
	v_mov_b32_e32 v136, v128
	v_mov_b32_e32 v137, v128
	v_mov_b32_e32 v138, v128
	v_mov_b32_e32 v139, v128
	v_mov_b32_e32 v144, v128
	v_mov_b32_e32 v145, v128
	v_mov_b32_e32 v146, v128
	v_mov_b32_e32 v147, v128
	v_mov_b32_e32 v228, v128
	v_mov_b32_e32 v229, v128
	v_mov_b32_e32 v230, v128
	v_mov_b32_e32 v231, v128
	v_mov_b32_e32 v232, v128
	v_mov_b32_e32 v233, v128
	v_mov_b32_e32 v234, v128
	v_mov_b32_e32 v235, v128
	s_branch .LBB0_165
	s_nop 0
; #define RAW_BARRIER() do { asm volatile("s_waitcnt lgkmcnt(0)" ::: "memory"); __builtin_amdgcn_s_barrier(); } while (0)
; #define GEMM_READ4(A_, B_, FA, FB) asm volatile( \
;         "ds_read_b128 %0, %6\n\tds_read_b128 %1, %6 offset:2048\n\tds_read_b128 %2, %6 offset:4096\n\tds_read_b128 %3, %6 offset:6144\n\t" \
;         "ds_read_b128 %4, %7\n\tds_read_b128 %5, %7 offset:2048" \
;         : "=&v"(FA[0]), "=&v"(FA[1]), "=&v"(FA[2]), "=&v"(FA[3]), "=&v"(FB[0]), "=&v"(FB[1]) : "v"(A_), "v"(B_) : "memory")
; #define GEMM_READ2(A_, B_, FA, FB) asm volatile( \
;         "ds_read_b128 %0, %4\n\tds_read_b128 %1, %4 offset:2048\n\tds_read_b128 %2, %5\n\tds_read_b128 %3, %5 offset:2048" \
;         : "=&v"(FA[0]), "=&v"(FA[1]), "=&v"(FB[0]), "=&v"(FB[1]) : "v"(A_), "v"(B_) : "memory")
; #define GEMM_WAIT4(FA, FB) asm volatile("s_waitcnt lgkmcnt(0)" : "+v"(FA[0]), "+v"(FA[1]), "+v"(FA[2]), "+v"(FA[3]), "+v"(FB[0]), "+v"(FB[1]) :: "memory")
; #define GEMM_WAIT2(FA, FB) asm volatile("s_waitcnt lgkmcnt(0)" : "+v"(FA[0]), "+v"(FA[1]), "+v"(FB[0]), "+v"(FB[1]) :: "memory")
; template <int WM, class Epi>
; DI void gemm_mfma(const bf16_t* __restrict__ A, const bf16_t* __restrict__ Bt, int Arows, int Brows, int MT, int NT, unsigned char* smem, int bid, int nb, int wave, Epi epi) {
;     ...
; #pragma unroll 1
;     for (int kt = 0; kt < NKT; ++kt) {
;       const int ahead = (NKT - 1 - kt < NST - 2) ? (NKT - 1 - kt) : (NST - 2);
;       if (NI == 4) { if (ahead == 2) asm volatile("s_waitcnt vmcnt(8)" ::: "memory"); else if (ahead == 1) asm volatile("s_waitcnt vmcnt(4)" ::: "memory"); else asm volatile("s_waitcnt vmcnt(0)" ::: "memory"); }
;       else { if (ahead == 1) asm volatile("s_waitcnt vmcnt(6)" ::: "memory"); else asm volatile("s_waitcnt vmcnt(0)" ::: "memory"); }
;       RAW_BARRIER();
;       if (kt + NST - 1 < NKT) issue(kt + NST - 1, (kt + NST - 1) % NST);
;       const unsigned sb = lds0 + (unsigned)((kt % NST) * STAGE);
;       const unsigned a0 = sb + offA0, a1 = sb + offA1, b0 = sb + offB0, b1 = sb + offB1;
;       if constexpr (WM == 4) GEMM_READ4(a0, b0, fa0, fb0); else GEMM_READ2(a0, b0, fa0, fb0);
;       GEMM_MMA(fa1, fb1);
;       if constexpr (WM == 4) { GEMM_WAIT4(fa0, fb0); GEMM_READ4(a1, b1, fa1, fb1); } else { GEMM_WAIT2(fa0, fb0); GEMM_READ2(a1, b1, fa1, fb1); }
;       GEMM_MMA(fa0, fb0);
;     }
.LBB0_165:
	s_waitcnt vmcnt(6)
	s_waitcnt lgkmcnt(0)
	s_add_i32 s6, s21, -2
	s_barrier
	s_cmp_gt_u32 s21, 31
	s_cbranch_scc1 .Lg16_tail
	s_setprio 1
	v_mfma_f32_16x16x32_bf16 v[0:3], v[128:131], v[144:147], v[0:3]
	s_mul_i32 s7, s21, 0xab
	s_bfe_u32 s7, s7, 0x70009
	s_mul_i32 s7, s7, 3
	s_sub_i32 s7, s21, s7
	s_and_b32 s7, s7, 0xff
	s_mulk_i32 s7, 0x6000
	s_add_i32 s25, s7, s9
	s_add_i32 s7, s7, s20
	s_mul_i32 s26, s6, 0xab
	s_bfe_u32 s26, s26, 0x70009
	s_mul_i32 s26, s26, 3
	s_sub_i32 s6, s6, s26
	s_and_b32 s6, s6, 0xff
	s_mulk_i32 s6, 0x6000
	v_add_u32_e32 v160, s6, v159
	v_add_u32_e32 v170, s6, v165
	ds_read_b128 v[196:199], v160
	ds_read_b128 v[200:203], v160 offset:1024
	v_mfma_f32_16x16x32_bf16 v[4:7], v[128:131], v[148:151], v[4:7]
	ds_read_b128 v[204:207], v160 offset:2048
	ds_read_b128 v[208:211], v160 offset:3072
	v_mfma_f32_16x16x32_bf16 v[8:11], v[128:131], v[228:231], v[8:11]
	ds_read_b128 v[212:215], v170
	ds_read_b128 v[216:219], v170 offset:1024
	v_mfma_f32_16x16x32_bf16 v[12:15], v[128:131], v[232:235], v[12:15]
	ds_read_b128 v[220:223], v170 offset:2048
	ds_read_b128 v[224:227], v170 offset:3072
	s_add_u32 s98, s0, 0x8c000
	s_addc_u32 s99, s1, 0
	s_add_u32 s100, s4, 0x2006000
	s_addc_u32 s101, s5, 0
	s_add_i32 m0, s7, 0x4000
	v_mfma_f32_16x16x32_bf16 v[16:19], v[132:135], v[144:147], v[16:19]
	global_load_lds_dwordx4 v154, s[98:99]
	v_mfma_f32_16x16x32_bf16 v[20:23], v[132:135], v[148:151], v[20:23]
	v_mfma_f32_16x16x32_bf16 v[24:27], v[132:135], v[228:231], v[24:27]
	global_load_lds_dwordx4 v154, s[98:99] offset:1024
	s_mov_b32 m0, s25
	v_mfma_f32_16x16x32_bf16 v[28:31], v[132:135], v[232:235], v[28:31]
	v_mfma_f32_16x16x32_bf16 v[32:35], v[136:139], v[144:147], v[32:35]
	global_load_lds_dwordx4 v154, s[100:101]
	v_mfma_f32_16x16x32_bf16 v[36:39], v[136:139], v[148:151], v[36:39]
	v_mfma_f32_16x16x32_bf16 v[40:43], v[136:139], v[228:231], v[40:43]
	global_load_lds_dwordx4 v154, s[100:101] offset:1024
	v_mfma_f32_16x16x32_bf16 v[44:47], v[136:139], v[232:235], v[44:47]
	v_mfma_f32_16x16x32_bf16 v[48:51], v[140:143], v[144:147], v[48:51]
	v_mfma_f32_16x16x32_bf16 v[52:55], v[140:143], v[148:151], v[52:55]
	v_mfma_f32_16x16x32_bf16 v[56:59], v[140:143], v[228:231], v[56:59]
	v_mfma_f32_16x16x32_bf16 v[60:63], v[140:143], v[232:235], v[60:63]
	s_setprio 0
	s_waitcnt lgkmcnt(0)
	ds_read_b128 v[128:131], v160 offset:4096
	ds_read_b128 v[132:135], v160 offset:5120
	ds_read_b128 v[136:139], v160 offset:6144
	ds_read_b128 v[140:143], v160 offset:7168
	s_setprio 1
	v_mfma_f32_16x16x32_bf16 v[64:67], v[196:199], v[212:215], v[64:67]
	v_mfma_f32_16x16x32_bf16 v[68:71], v[196:199], v[216:219], v[68:71]
	global_load_lds_dwordx4 v154, s[100:101] offset:2048
	v_mfma_f32_16x16x32_bf16 v[72:75], v[196:199], v[220:223], v[72:75]
	v_mfma_f32_16x16x32_bf16 v[76:79], v[196:199], v[224:227], v[76:79]
	v_mfma_f32_16x16x32_bf16 v[80:83], v[200:203], v[212:215], v[80:83]
	global_load_lds_dwordx4 v154, s[100:101] offset:3072
	v_mfma_f32_16x16x32_bf16 v[84:87], v[200:203], v[216:219], v[84:87]
	v_mfma_f32_16x16x32_bf16 v[88:91], v[200:203], v[220:223], v[88:91]
	v_mfma_f32_16x16x32_bf16 v[92:95], v[200:203], v[224:227], v[92:95]
	v_mfma_f32_16x16x32_bf16 v[96:99], v[204:207], v[212:215], v[96:99]
	v_mfma_f32_16x16x32_bf16 v[100:103], v[204:207], v[216:219], v[100:103]
	v_mfma_f32_16x16x32_bf16 v[104:107], v[204:207], v[220:223], v[104:107]
	v_mfma_f32_16x16x32_bf16 v[108:111], v[204:207], v[224:227], v[108:111]
	v_mfma_f32_16x16x32_bf16 v[112:115], v[208:211], v[212:215], v[112:115]
	v_mfma_f32_16x16x32_bf16 v[116:119], v[208:211], v[216:219], v[116:119]
	v_mfma_f32_16x16x32_bf16 v[120:123], v[208:211], v[220:223], v[120:123]
	v_mfma_f32_16x16x32_bf16 v[124:127], v[208:211], v[224:227], v[124:127]
	s_setprio 0
	s_add_u32 s0, s0, 0x46000
	s_addc_u32 s1, s1, 0
	s_add_u32 s4, s4, 0x120000
	s_addc_u32 s5, s5, 0
	s_add_i32 s21, s21, 1
	s_waitcnt vmcnt(6)
	s_waitcnt lgkmcnt(0)
	s_add_i32 s6, s21, -2
	s_barrier
; #define RAW_BARRIER() do { asm volatile("s_waitcnt lgkmcnt(0)" ::: "memory"); __builtin_amdgcn_s_barrier(); } while (0)
; #define GEMM_READ4(A_, B_, FA, FB) asm volatile( \
;         "ds_read_b128 %0, %6\n\tds_read_b128 %1, %6 offset:2048\n\tds_read_b128 %2, %6 offset:4096\n\tds_read_b128 %3, %6 offset:6144\n\t" \
;         "ds_read_b128 %4, %7\n\tds_read_b128 %5, %7 offset:2048" \
;         : "=&v"(FA[0]), "=&v"(FA[1]), "=&v"(FA[2]), "=&v"(FA[3]), "=&v"(FB[0]), "=&v"(FB[1]) : "v"(A_), "v"(B_) : "memory")
; #define GEMM_READ2(A_, B_, FA, FB) asm volatile( \
;         "ds_read_b128 %0, %4\n\tds_read_b128 %1, %4 offset:2048\n\tds_read_b128 %2, %5\n\tds_read_b128 %3, %5 offset:2048" \
;         : "=&v"(FA[0]), "=&v"(FA[1]), "=&v"(FB[0]), "=&v"(FB[1]) : "v"(A_), "v"(B_) : "memory")
; #define GEMM_WAIT4(FA, FB) asm volatile("s_waitcnt lgkmcnt(0)" : "+v"(FA[0]), "+v"(FA[1]), "+v"(FA[2]), "+v"(FA[3]), "+v"(FB[0]), "+v"(FB[1]) :: "memory")
; #define GEMM_WAIT2(FA, FB) asm volatile("s_waitcnt lgkmcnt(0)" : "+v"(FA[0]), "+v"(FA[1]), "+v"(FB[0]), "+v"(FB[1]) :: "memory")
; template <int WM, class Epi>
; DI void gemm_mfma(const bf16_t* __restrict__ A, const bf16_t* __restrict__ Bt, int Arows, int Brows, int MT, int NT, unsigned char* smem, int bid, int nb, int wave, Epi epi) {
;     ...
; #pragma unroll 1
;     for (int kt = 0; kt < NKT; ++kt) {
;       const int ahead = (NKT - 1 - kt < NST - 2) ? (NKT - 1 - kt) : (NST - 2);
;       if (NI == 4) { if (ahead == 2) asm volatile("s_waitcnt vmcnt(8)" ::: "memory"); else if (ahead == 1) asm volatile("s_waitcnt vmcnt(4)" ::: "memory"); else asm volatile("s_waitcnt vmcnt(0)" ::: "memory"); }
;       else { if (ahead == 1) asm volatile("s_waitcnt vmcnt(6)" ::: "memory"); else asm volatile("s_waitcnt vmcnt(0)" ::: "memory"); }
;       RAW_BARRIER();
;       if (kt + NST - 1 < NKT) issue(kt + NST - 1, (kt + NST - 1) % NST);
;       const unsigned sb = lds0 + (unsigned)((kt % NST) * STAGE);
;       const unsigned a0 = sb + offA0, a1 = sb + offA1, b0 = sb + offB0, b1 = sb + offB1;
;       if constexpr (WM == 4) GEMM_READ4(a0, b0, fa0, fb0); else GEMM_READ2(a0, b0, fa0, fb0);
;       GEMM_MMA(fa1, fb1);
;       if constexpr (WM == 4) { GEMM_WAIT4(fa0, fb0); GEMM_READ4(a1, b1, fa1, fb1); } else { GEMM_WAIT2(fa0, fb0); GEMM_READ2(a1, b1, fa1, fb1); }
;       GEMM_MMA(fa0, fb0);
;     }
	s_setprio 1
	v_mfma_f32_16x16x32_bf16 v[0:3], v[128:131], v[212:215], v[0:3]
	s_mul_i32 s7, s21, 0xab
	s_bfe_u32 s7, s7, 0x70009
	s_mul_i32 s7, s7, 3
	s_sub_i32 s7, s21, s7
	s_and_b32 s7, s7, 0xff
	s_mulk_i32 s7, 0x6000
	s_add_i32 s25, s7, s9
	s_add_i32 s7, s7, s20
	s_mul_i32 s26, s6, 0xab
	s_bfe_u32 s26, s26, 0x70009
	s_mul_i32 s26, s26, 3
	s_sub_i32 s6, s6, s26
	s_and_b32 s6, s6, 0xff
	s_mulk_i32 s6, 0x6000
	v_add_u32_e32 v160, s6, v159
	v_add_u32_e32 v170, s6, v165
	ds_read_b128 v[196:199], v160
	ds_read_b128 v[200:203], v160 offset:1024
	v_mfma_f32_16x16x32_bf16 v[4:7], v[128:131], v[216:219], v[4:7]
	ds_read_b128 v[204:207], v160 offset:2048
	ds_read_b128 v[208:211], v160 offset:3072
	v_mfma_f32_16x16x32_bf16 v[8:11], v[128:131], v[220:223], v[8:11]
	ds_read_b128 v[144:147], v170
	ds_read_b128 v[148:151], v170 offset:1024
	v_mfma_f32_16x16x32_bf16 v[12:15], v[128:131], v[224:227], v[12:15]
	ds_read_b128 v[228:231], v170 offset:2048
	ds_read_b128 v[232:235], v170 offset:3072
	s_add_u32 s98, s0, 0x8c000
	s_addc_u32 s99, s1, 0
	s_add_u32 s100, s4, 0x2006000
	s_addc_u32 s101, s5, 0
	s_add_i32 m0, s7, 0x4000
	v_mfma_f32_16x16x32_bf16 v[16:19], v[132:135], v[212:215], v[16:19]
	global_load_lds_dwordx4 v154, s[98:99]
	v_mfma_f32_16x16x32_bf16 v[20:23], v[132:135], v[216:219], v[20:23]
	v_mfma_f32_16x16x32_bf16 v[24:27], v[132:135], v[220:223], v[24:27]
	global_load_lds_dwordx4 v154, s[98:99] offset:1024
	s_mov_b32 m0, s25
	v_mfma_f32_16x16x32_bf16 v[28:31], v[132:135], v[224:227], v[28:31]
	v_mfma_f32_16x16x32_bf16 v[32:35], v[136:139], v[212:215], v[32:35]
	global_load_lds_dwordx4 v154, s[100:101]
	v_mfma_f32_16x16x32_bf16 v[36:39], v[136:139], v[216:219], v[36:39]
	v_mfma_f32_16x16x32_bf16 v[40:43], v[136:139], v[220:223], v[40:43]
	global_load_lds_dwordx4 v154, s[100:101] offset:1024
	v_mfma_f32_16x16x32_bf16 v[44:47], v[136:139], v[224:227], v[44:47]
	v_mfma_f32_16x16x32_bf16 v[48:51], v[140:143], v[212:215], v[48:51]
	v_mfma_f32_16x16x32_bf16 v[52:55], v[140:143], v[216:219], v[52:55]
	v_mfma_f32_16x16x32_bf16 v[56:59], v[140:143], v[220:223], v[56:59]
	v_mfma_f32_16x16x32_bf16 v[60:63], v[140:143], v[224:227], v[60:63]
	s_setprio 0
	s_waitcnt lgkmcnt(0)
	ds_read_b128 v[128:131], v160 offset:4096
	ds_read_b128 v[132:135], v160 offset:5120
	ds_read_b128 v[136:139], v160 offset:6144
	ds_read_b128 v[140:143], v160 offset:7168
	s_setprio 1
	v_mfma_f32_16x16x32_bf16 v[64:67], v[196:199], v[144:147], v[64:67]
	v_mfma_f32_16x16x32_bf16 v[68:71], v[196:199], v[148:151], v[68:71]
	global_load_lds_dwordx4 v154, s[100:101] offset:2048
	v_mfma_f32_16x16x32_bf16 v[72:75], v[196:199], v[228:231], v[72:75]
	v_mfma_f32_16x16x32_bf16 v[76:79], v[196:199], v[232:235], v[76:79]
	v_mfma_f32_16x16x32_bf16 v[80:83], v[200:203], v[144:147], v[80:83]
	global_load_lds_dwordx4 v154, s[100:101] offset:3072
	v_mfma_f32_16x16x32_bf16 v[84:87], v[200:203], v[148:151], v[84:87]
	v_mfma_f32_16x16x32_bf16 v[88:91], v[200:203], v[228:231], v[88:91]
	v_mfma_f32_16x16x32_bf16 v[92:95], v[200:203], v[232:235], v[92:95]
	v_mfma_f32_16x16x32_bf16 v[96:99], v[204:207], v[144:147], v[96:99]
	v_mfma_f32_16x16x32_bf16 v[100:103], v[204:207], v[148:151], v[100:103]
	v_mfma_f32_16x16x32_bf16 v[104:107], v[204:207], v[228:231], v[104:107]
	v_mfma_f32_16x16x32_bf16 v[108:111], v[204:207], v[232:235], v[108:111]
	v_mfma_f32_16x16x32_bf16 v[112:115], v[208:211], v[144:147], v[112:115]
	v_mfma_f32_16x16x32_bf16 v[116:119], v[208:211], v[148:151], v[116:119]
	v_mfma_f32_16x16x32_bf16 v[120:123], v[208:211], v[228:231], v[120:123]
	v_mfma_f32_16x16x32_bf16 v[124:127], v[208:211], v[232:235], v[124:127]
	s_setprio 0
	s_add_u32 s0, s0, 0x46000
	s_addc_u32 s1, s1, 0
	s_add_u32 s4, s4, 0x120000
	s_addc_u32 s5, s5, 0
	s_add_i32 s21, s21, 1
	s_branch .LBB0_165
	s_nop 0
